# P0 row loop: rows prefetched one iteration ahead into spare registers (first pair issued at P0 start)
# speedup vs baseline: 1.2994x; 1.0034x over previous
.LBB0_30:
	s_or_b64 exec, exec, s[6:7]
	s_lshl_b32 s4, s2, 3
	s_add_i32 s46, s44, s4
	s_waitcnt lgkmcnt(0)
	s_lshl_b32 s3, s3, 3
	v_readlane_b32 s8, v233, 11
	v_readlane_b32 s9, v233, 12
	s_nop 4
	v_lshlrev_b32_e32 v124, 4, v218
	s_lshl_b32 s6, s46, 12
	v_add_u32_e32 v125, s6, v124
	global_load_dwordx4 v[92:95], v125, s[8:9]
	global_load_dwordx4 v[96:99], v125, s[8:9] offset:1024
	global_load_dwordx4 v[100:103], v125, s[8:9] offset:2048
	global_load_dwordx4 v[104:107], v125, s[8:9] offset:3072
	s_add_i32 s6, s46, s3
	s_min_i32 s6, s6, 0x3fff
	s_lshl_b32 s6, s6, 12
	v_add_u32_e32 v125, s6, v124
	global_load_dwordx4 v[108:111], v125, s[8:9]
	global_load_dwordx4 v[112:115], v125, s[8:9] offset:1024
	global_load_dwordx4 v[116:119], v125, s[8:9] offset:2048
	global_load_dwordx4 v[120:123], v125, s[8:9] offset:3072
	s_cmpk_gt_i32 s46, 0x6ff
	s_cbranch_scc1 .LBB0_33
	s_mul_i32 s4, s44, 0x2400
	v_and_b32_e32 v0, 31, v188
	v_readlane_b32 s12, v233, 11
	s_add_i32 s4, s4, 0
	v_lshlrev_b32_e32 v2, 2, v0
	v_mov_b32_e32 v3, 0
	v_readlane_b32 s16, v233, 15
	v_readlane_b32 s17, v233, 16
	v_lshrrev_b32_e32 v4, 5, v218
	v_add_u32_e32 v7, s4, v2
	v_lshl_add_u64 v[0:1], s[16:17], 0, v[2:3]
	v_lshlrev_b32_e32 v2, 3, v188
	v_mul_u32_u24_e32 v8, 0x84, v4
	v_lshrrev_b32_e32 v5, 3, v218
	v_and_b32_e32 v2, 56, v2
	v_mul_u32_u24_e32 v6, 0x84, v2
	v_lshlrev_b32_e32 v2, 1, v2
	v_lshlrev_b32_e32 v9, 2, v5
	v_add_u32_e32 v7, v7, v8
	v_lshl_add_u64 v[2:3], s[54:55], 0, v[2:3]
	v_add3_u32 v6, s4, v6, v9
	s_lshl_b32 s4, s46, 5
	s_lshl_b32 s5, s3, 5
	s_movk_i32 s8, 0x3820
	v_add_u32_e32 v8, 0x400, v7
	v_add_u32_e32 v9, 0x800, v7
	v_add_u32_e32 v10, 0xc00, v7
	v_add_u32_e32 v11, 0x1000, v7
	v_add_u32_e32 v12, 0x1400, v7
	v_add_u32_e32 v13, 0x1800, v7
	v_add_u32_e32 v14, 0x1c00, v7
	s_mov_b32 s9, s46
	v_readlane_b32 s13, v233, 12
	v_readlane_b32 s14, v233, 13
	v_readlane_b32 s15, v233, 14
	v_readlane_b32 s18, v233, 17
	v_readlane_b32 s19, v233, 18
	v_readlane_b32 s20, v233, 19
	v_readlane_b32 s21, v233, 20
	v_readlane_b32 s22, v233, 21
	v_readlane_b32 s23, v233, 22
	v_readlane_b32 s24, v233, 23
	v_readlane_b32 s25, v233, 24
	v_readlane_b32 s26, v233, 25
	v_readlane_b32 s27, v233, 26

.LBB0_33:
	s_cmpk_gt_i32 s46, 0x3fff
	s_barrier
	s_cbranch_scc1 .LBB0_44
	v_mov_b32_e32 v33, 0
	v_lshlrev_b32_e32 v32, 4, v218
	v_readlane_b32 s12, v233, 11
	v_lshlrev_b32_e32 v0, 3, v218
	v_mov_b32_e32 v1, v33
	s_add_u32 s4, s48, 0x100000
	v_readlane_b32 s13, v233, 12
	v_readlane_b32 s14, v233, 13
	v_readlane_b32 s15, v233, 14
	v_lshl_add_u64 v[38:39], s[34:35], 0, v[0:1]
	v_add_u32_e32 v0, 0, v32
	s_addc_u32 s5, s49, 0
	v_lshl_add_u64 v[34:35], s[14:15], 0, v[32:33]
	v_lshl_add_u64 v[36:37], s[12:13], 0, v[32:33]
	v_cmp_eq_u32_e32 vcc, 0, v218
	v_cmp_ne_u32_e64 s[6:7], 0, v218
	v_mov_b32_e32 v56, 0x358637bd
	s_mov_b32 s52, 0x800000
	v_add_u32_e32 v57, 0x12000, v0
	v_readlane_b32 s16, v233, 15
	v_readlane_b32 s17, v233, 16
	v_readlane_b32 s18, v233, 17
	v_readlane_b32 s19, v233, 18
	v_readlane_b32 s20, v233, 19
	v_readlane_b32 s21, v233, 20
	v_readlane_b32 s22, v233, 21
	v_readlane_b32 s23, v233, 22
	v_readlane_b32 s24, v233, 23
	v_readlane_b32 s25, v233, 24
	v_readlane_b32 s26, v233, 25
	v_readlane_b32 s27, v233, 26
	global_load_dwordx4 v[76:79], v[34:35], off
	global_load_dwordx4 v[80:83], v[34:35], off offset:1024
	global_load_dwordx4 v[84:87], v[34:35], off offset:2048
	global_load_dwordx4 v[88:91], v[34:35], off offset:3072
	s_waitcnt vmcnt(0)
	s_branch .LBB0_37

.LBB0_37:
	s_ashr_i32 s47, s46, 31
	ds_read_b128 v[40:43], v57
	ds_read_b128 v[44:47], v57 offset:1024
	ds_read_b128 v[48:51], v57 offset:2048
	ds_read_b128 v[52:55], v57 offset:3072
	ds_read_b128 v[58:61], v57 offset:4096
	ds_read_b128 v[62:65], v57 offset:5120
	s_add_i32 s14, s46, s3
	s_waitcnt vmcnt(12)
	v_mov_b64_e32 v[28:29], v[92:93]
	v_mov_b64_e32 v[30:31], v[94:95]
	v_mov_b64_e32 v[24:25], v[96:97]
	v_mov_b64_e32 v[26:27], v[98:99]
	v_mov_b64_e32 v[20:21], v[100:101]
	v_mov_b64_e32 v[22:23], v[102:103]
	v_mov_b64_e32 v[16:17], v[104:105]
	v_mov_b64_e32 v[18:19], v[106:107]
	v_mov_b64_e32 v[12:13], v[108:109]
	v_mov_b64_e32 v[14:15], v[110:111]
	v_mov_b64_e32 v[8:9], v[112:113]
	v_mov_b64_e32 v[10:11], v[114:115]
	v_mov_b64_e32 v[4:5], v[116:117]
	v_mov_b64_e32 v[6:7], v[118:119]
	v_mov_b64_e32 v[0:1], v[120:121]
	v_mov_b64_e32 v[2:3], v[122:123]
	s_add_i32 s8, s14, s3
	s_min_i32 s8, s8, 0x3fff
	s_ashr_i32 s9, s8, 31
	s_lshl_b64 s[8:9], s[8:9], 12
	v_lshl_add_u64 v[124:125], v[36:37], 0, s[8:9]
	global_load_dwordx4 v[92:95], v[124:125], off
	global_load_dwordx4 v[96:99], v[124:125], off offset:1024
	global_load_dwordx4 v[100:103], v[124:125], off offset:2048
	global_load_dwordx4 v[104:107], v[124:125], off offset:3072
	s_add_i32 s8, s14, s3
	s_add_i32 s8, s8, s3
	s_min_i32 s8, s8, 0x3fff
	s_ashr_i32 s9, s8, 31
	s_lshl_b64 s[8:9], s[8:9], 12
	v_lshl_add_u64 v[124:125], v[36:37], 0, s[8:9]
	global_load_dwordx4 v[108:111], v[124:125], off
	global_load_dwordx4 v[112:115], v[124:125], off offset:1024
	global_load_dwordx4 v[116:119], v[124:125], off offset:2048
	global_load_dwordx4 v[120:123], v[124:125], off offset:3072
	v_mul_f32_e32 v32, v29, v29
	v_mul_f32_e32 v66, v31, v31
	v_mul_f32_e32 v67, v25, v25
	v_mul_f32_e32 v68, v27, v27
	v_mul_f32_e32 v69, v21, v21
	v_mul_f32_e32 v70, v23, v23
	s_waitcnt lgkmcnt(5)
	v_mul_f32_e32 v41, v29, v41
	v_fmac_f32_e32 v32, v28, v28
	v_fmac_f32_e32 v66, v30, v30
	v_fmac_f32_e32 v67, v24, v24
	v_fmac_f32_e32 v68, v26, v26
	v_mul_f32_e32 v71, v17, v17
	v_mul_f32_e32 v72, v19, v19
	v_mul_f32_e32 v43, v31, v43
	v_fmac_f32_e32 v69, v20, v20
	v_fmac_f32_e32 v70, v22, v22
	v_fmac_f32_e32 v41, v28, v40
	v_add_f32_e32 v32, v32, v66
	v_add_f32_e32 v40, v67, v68
	s_waitcnt lgkmcnt(4)
	v_mul_f32_e32 v45, v25, v45
	v_fmac_f32_e32 v71, v16, v16
	v_fmac_f32_e32 v72, v18, v18
	v_fmac_f32_e32 v43, v30, v42
	v_add_f32_e32 v42, v69, v70
	v_add_f32_e32 v32, v32, v40
	v_fmac_f32_e32 v45, v24, v44
	v_add_f32_e32 v44, v71, v72
	v_add_f32_e32 v32, v32, v42
	v_add_f32_e32 v32, v32, v44
	v_mul_f32_e32 v47, v27, v47
	s_waitcnt lgkmcnt(3)
	v_mul_f32_e32 v49, v21, v49
	v_add_f32_dpp v32, v32, v32 quad_perm:[1,0,3,2] row_mask:0xf bank_mask:0xf bound_ctrl:1
	v_mul_f32_e32 v51, v23, v51
	v_fmac_f32_e32 v47, v26, v46
	v_add_f32_dpp v32, v32, v32 quad_perm:[2,3,0,1] row_mask:0xf bank_mask:0xf bound_ctrl:1
	v_add_f32_e32 v41, v41, v43
	s_waitcnt lgkmcnt(2)
	v_mul_f32_e32 v53, v17, v53
	v_add_f32_dpp v32, v32, v32 row_half_mirror row_mask:0xf bank_mask:0xf bound_ctrl:1
	v_mul_f32_e32 v55, v19, v55
	v_fmac_f32_e32 v49, v20, v48
	v_add_f32_dpp v32, v32, v32 row_mirror row_mask:0xf bank_mask:0xf bound_ctrl:1
	v_mov_b32_e32 v42, v32
	s_nop 1
	v_permlane16_swap_b32_e32 v32, v42
	v_add_f32_e32 v32, v32, v42
	v_fmac_f32_e32 v51, v22, v50
	v_add_f32_e32 v43, v45, v47
	v_add_f32_e32 v40, 0, v41
	v_mov_b32_e32 v42, v32
	v_fmac_f32_e32 v53, v16, v52
	v_fmac_f32_e32 v55, v18, v54
	v_add_f32_e32 v45, v49, v51
	v_add_f32_e32 v40, v40, v43
	v_permlane32_swap_b32_e32 v32, v42
	v_add_f32_e32 v46, v53, v55
	v_add_f32_e32 v40, v40, v45
	v_add_f32_e32 v32, v32, v42
	v_add_f32_e32 v40, v40, v46
	v_fmamk_f32 v32, v32, 0x3a800000, v56
	s_waitcnt lgkmcnt(1)
	v_mul_f32_e32 v59, v29, v59
	v_mul_f32_e32 v61, v31, v61
	v_add_f32_dpp v40, v40, v40 quad_perm:[1,0,3,2] row_mask:0xf bank_mask:0xf bound_ctrl:1
	v_mul_f32_e32 v42, 0x4b800000, v32
	v_cmp_gt_f32_e64 s[8:9], s52, v32
	v_fmac_f32_e32 v59, v28, v58
	v_fmac_f32_e32 v61, v30, v60
	v_add_f32_dpp v40, v40, v40 quad_perm:[2,3,0,1] row_mask:0xf bank_mask:0xf bound_ctrl:1
	v_cndmask_b32_e64 v32, v32, v42, s[8:9]
	v_add_f32_e32 v47, v59, v61
	v_add_f32_dpp v40, v40, v40 row_half_mirror row_mask:0xf bank_mask:0xf bound_ctrl:1
	v_rsq_f32_e32 v32, v32
	v_add_f32_e32 v41, 0, v47
	v_add_f32_dpp v40, v40, v40 row_mirror row_mask:0xf bank_mask:0xf bound_ctrl:1
	ds_read_b128 v[44:47], v57 offset:6144
	ds_read_b128 v[48:51], v57 offset:7168
	v_mov_b32_e32 v43, v40
	s_waitcnt lgkmcnt(2)
	v_mul_f32_e32 v63, v25, v63
	v_mul_f32_e32 v65, v27, v65
	v_permlane16_swap_b32_e32 v40, v43
	v_fmac_f32_e32 v63, v24, v62
	v_add_f32_e32 v40, v40, v43
	v_mul_f32_e32 v43, 0x45800000, v32
	v_fmac_f32_e32 v65, v26, v64
	v_cndmask_b32_e64 v32, v32, v43, s[8:9]
	v_add_f32_e32 v43, v63, v65
	v_add_f32_e32 v41, v41, v43
	s_waitcnt lgkmcnt(1)
	v_mul_f32_e32 v43, v21, v45
	v_fmac_f32_e32 v43, v20, v44
	v_mul_f32_e32 v44, v23, v47
	v_fmac_f32_e32 v44, v22, v46
	v_add_f32_e32 v43, v43, v44
	v_add_f32_e32 v41, v41, v43
	s_waitcnt lgkmcnt(0)
	v_mul_f32_e32 v43, v17, v49
	v_mul_f32_e32 v44, v19, v51
	v_fmac_f32_e32 v43, v16, v48
	v_fmac_f32_e32 v44, v18, v50
	v_add_f32_e32 v43, v43, v44
	ds_read_b128 v[44:47], v57 offset:8192
	ds_read_b128 v[48:51], v57 offset:9216
	v_add_f32_e32 v41, v41, v43
	v_mov_b32_e32 v42, v40
	s_nop 1
	v_permlane32_swap_b32_e32 v40, v42
	s_waitcnt lgkmcnt(1)
	v_mul_f32_e32 v45, v29, v45
	v_fmac_f32_e32 v45, v28, v44
	v_mul_f32_e32 v44, v31, v47
	v_fmac_f32_e32 v44, v30, v46
	v_add_f32_e32 v44, v45, v44
	s_waitcnt lgkmcnt(0)
	v_mul_f32_e32 v49, v25, v49
	v_add_f32_e32 v52, 0, v44
	v_fmac_f32_e32 v49, v24, v48
	v_mul_f32_e32 v48, v27, v51
	ds_read_b128 v[44:47], v57 offset:10240
	v_fmac_f32_e32 v48, v26, v50
	v_add_f32_e32 v48, v49, v48
	v_add_f32_e32 v52, v52, v48
	ds_read_b128 v[48:51], v57 offset:11264
	s_waitcnt lgkmcnt(1)
	v_mul_f32_e32 v45, v21, v45
	v_fmac_f32_e32 v45, v20, v44
	v_mul_f32_e32 v44, v23, v47
	v_fmac_f32_e32 v44, v22, v46
	v_add_f32_e32 v44, v45, v44
	s_waitcnt lgkmcnt(0)
	v_mul_f32_e32 v45, v17, v49
	v_mul_f32_e32 v46, v19, v51
	v_fmac_f32_e32 v45, v16, v48
	v_fmac_f32_e32 v46, v18, v50
	v_add_f32_e32 v44, v52, v44
	v_add_f32_e32 v45, v45, v46
	v_add_f32_e32 v44, v44, v45
	ds_read_b128 v[48:51], v57 offset:12288
	ds_read_b128 v[52:55], v57 offset:13312
	v_add_f32_dpp v44, v44, v44 quad_perm:[1,0,3,2] row_mask:0xf bank_mask:0xf bound_ctrl:1
	v_add_f32_dpp v41, v41, v41 quad_perm:[1,0,3,2] row_mask:0xf bank_mask:0xf bound_ctrl:1
	s_waitcnt lgkmcnt(1)
	v_mul_f32_e32 v47, v31, v51
	v_add_f32_dpp v44, v44, v44 quad_perm:[2,3,0,1] row_mask:0xf bank_mask:0xf bound_ctrl:1
	v_fmac_f32_e32 v47, v30, v50
	v_add_f32_dpp v41, v41, v41 quad_perm:[2,3,0,1] row_mask:0xf bank_mask:0xf bound_ctrl:1
	v_add_f32_dpp v44, v44, v44 row_half_mirror row_mask:0xf bank_mask:0xf bound_ctrl:1
	s_nop 0
	v_add_f32_dpp v41, v41, v41 row_half_mirror row_mask:0xf bank_mask:0xf bound_ctrl:1
	v_add_f32_dpp v44, v44, v44 row_mirror row_mask:0xf bank_mask:0xf bound_ctrl:1
	v_mov_b32_e32 v45, v44
	s_nop 1
	v_permlane16_swap_b32_e32 v44, v45
	v_add_f32_e32 v44, v44, v45
	v_mul_f32_e32 v45, v29, v49
	v_fmac_f32_e32 v45, v28, v48
	ds_read_b128 v[48:51], v57 offset:14336
	v_add_f32_e32 v45, v45, v47
	s_waitcnt lgkmcnt(1)
	v_mul_f32_e32 v47, v25, v53
	v_fmac_f32_e32 v47, v24, v52
	v_mul_f32_e32 v52, v27, v55
	v_fmac_f32_e32 v52, v26, v54
	v_add_f32_e32 v45, 0, v45
	v_add_f32_e32 v47, v47, v52
	ds_read_b128 v[52:55], v57 offset:15360
	v_add_f32_e32 v45, v45, v47
	s_waitcnt lgkmcnt(1)
	v_mul_f32_e32 v47, v21, v49
	v_fmac_f32_e32 v47, v20, v48
	v_mul_f32_e32 v48, v23, v51
	v_fmac_f32_e32 v48, v22, v50
	v_add_f32_e32 v47, v47, v48
	v_add_f32_e32 v45, v45, v47
	s_waitcnt lgkmcnt(0)
	v_mul_f32_e32 v47, v17, v53
	v_mul_f32_e32 v48, v19, v55
	v_fmac_f32_e32 v47, v16, v52
	v_fmac_f32_e32 v48, v18, v54
	v_add_f32_e32 v47, v47, v48
	ds_read_b128 v[48:51], v57 offset:16384
	ds_read_b128 v[52:55], v57 offset:17408
	v_add_f32_e32 v45, v45, v47
	v_add_f32_dpp v41, v41, v41 row_mirror row_mask:0xf bank_mask:0xf bound_ctrl:1
	v_mov_b32_e32 v43, v41
	s_waitcnt lgkmcnt(1)
	v_mul_f32_e32 v49, v29, v49
	v_fmac_f32_e32 v49, v28, v48
	v_mul_f32_e32 v48, v31, v51
	v_fmac_f32_e32 v48, v30, v50
	v_add_f32_e32 v48, v49, v48
	s_waitcnt lgkmcnt(0)
	v_mul_f32_e32 v53, v25, v53
	v_add_f32_e32 v58, 0, v48
	v_fmac_f32_e32 v53, v24, v52
	v_mul_f32_e32 v52, v27, v55
	ds_read_b128 v[48:51], v57 offset:18432
	v_fmac_f32_e32 v52, v26, v54
	v_add_f32_e32 v52, v53, v52
	v_add_f32_e32 v58, v58, v52
	ds_read_b128 v[52:55], v57 offset:19456
	s_waitcnt lgkmcnt(1)
	v_mul_f32_e32 v49, v21, v49
	v_fmac_f32_e32 v49, v20, v48
	v_mul_f32_e32 v48, v23, v51
	v_fmac_f32_e32 v48, v22, v50
	v_add_f32_e32 v48, v49, v48
	s_waitcnt lgkmcnt(0)
	v_mul_f32_e32 v49, v17, v53
	v_mul_f32_e32 v50, v19, v55
	v_fmac_f32_e32 v49, v16, v52
	v_fmac_f32_e32 v50, v18, v54
	v_add_f32_e32 v48, v58, v48
	v_add_f32_e32 v49, v49, v50
	v_add_f32_e32 v48, v48, v49
	ds_read_b128 v[52:55], v57 offset:20480
	ds_read_b128 v[58:61], v57 offset:21504
	v_add_f32_dpp v48, v48, v48 quad_perm:[1,0,3,2] row_mask:0xf bank_mask:0xf bound_ctrl:1
	v_add_f32_dpp v45, v45, v45 quad_perm:[1,0,3,2] row_mask:0xf bank_mask:0xf bound_ctrl:1
	v_permlane16_swap_b32_e32 v41, v43
	v_add_f32_dpp v48, v48, v48 quad_perm:[2,3,0,1] row_mask:0xf bank_mask:0xf bound_ctrl:1
	s_waitcnt lgkmcnt(1)
	v_mul_f32_e32 v51, v31, v55
	v_fmac_f32_e32 v51, v30, v54
	v_add_f32_dpp v48, v48, v48 row_half_mirror row_mask:0xf bank_mask:0xf bound_ctrl:1
	v_add_f32_dpp v45, v45, v45 quad_perm:[2,3,0,1] row_mask:0xf bank_mask:0xf bound_ctrl:1
	v_add_f32_e32 v41, v41, v43
	v_add_f32_dpp v48, v48, v48 row_mirror row_mask:0xf bank_mask:0xf bound_ctrl:1
	v_mov_b32_e32 v49, v48
	s_nop 1
	v_permlane16_swap_b32_e32 v48, v49
	v_add_f32_e32 v48, v48, v49
	v_mul_f32_e32 v49, v29, v53
	v_fmac_f32_e32 v49, v28, v52
	ds_read_b128 v[52:55], v57 offset:22528
	v_add_f32_e32 v49, v49, v51
	s_waitcnt lgkmcnt(1)
	v_mul_f32_e32 v51, v25, v59
	v_fmac_f32_e32 v51, v24, v58
	v_mul_f32_e32 v58, v27, v61
	v_fmac_f32_e32 v58, v26, v60
	v_add_f32_e32 v49, 0, v49
	v_add_f32_e32 v51, v51, v58
	ds_read_b128 v[58:61], v57 offset:23552
	v_add_f32_e32 v49, v49, v51
	s_waitcnt lgkmcnt(1)
	v_mul_f32_e32 v51, v21, v53
	v_fmac_f32_e32 v51, v20, v52
	v_mul_f32_e32 v52, v23, v55
	v_fmac_f32_e32 v52, v22, v54
	v_add_f32_e32 v51, v51, v52
	v_add_f32_e32 v49, v49, v51
	s_waitcnt lgkmcnt(0)
	v_mul_f32_e32 v51, v17, v59
	v_mul_f32_e32 v52, v19, v61
	v_fmac_f32_e32 v51, v16, v58
	v_fmac_f32_e32 v52, v18, v60
	v_add_f32_e32 v51, v51, v52
	ds_read_b128 v[52:55], v57 offset:24576
	ds_read_b128 v[58:61], v57 offset:25600
	v_add_f32_e32 v49, v49, v51
	v_add_f32_dpp v45, v45, v45 row_half_mirror row_mask:0xf bank_mask:0xf bound_ctrl:1
	v_mov_b32_e32 v43, v41
	s_waitcnt lgkmcnt(1)
	v_mul_f32_e32 v53, v29, v53
	v_fmac_f32_e32 v53, v28, v52
	v_mul_f32_e32 v52, v31, v55
	v_fmac_f32_e32 v52, v30, v54
	v_add_f32_e32 v52, v53, v52
	s_waitcnt lgkmcnt(0)
	v_mul_f32_e32 v59, v25, v59
	v_add_f32_e32 v62, 0, v52
	v_fmac_f32_e32 v59, v24, v58
	v_mul_f32_e32 v58, v27, v61
	ds_read_b128 v[52:55], v57 offset:26624
	v_fmac_f32_e32 v58, v26, v60
	v_add_f32_e32 v58, v59, v58
	v_add_f32_e32 v62, v62, v58
	ds_read_b128 v[58:61], v57 offset:27648
	s_waitcnt lgkmcnt(1)
	v_mul_f32_e32 v53, v21, v53
	v_fmac_f32_e32 v53, v20, v52
	v_mul_f32_e32 v52, v23, v55
	v_fmac_f32_e32 v52, v22, v54
	v_add_f32_e32 v52, v53, v52
	s_waitcnt lgkmcnt(0)
	v_mul_f32_e32 v53, v17, v59
	v_mul_f32_e32 v54, v19, v61
	v_fmac_f32_e32 v53, v16, v58
	v_fmac_f32_e32 v54, v18, v60
	v_add_f32_e32 v52, v62, v52
	v_add_f32_e32 v53, v53, v54
	v_add_f32_e32 v52, v52, v53
	ds_read_b128 v[58:61], v57 offset:28672
	ds_read_b128 v[62:65], v57 offset:29696
	v_add_f32_dpp v52, v52, v52 quad_perm:[1,0,3,2] row_mask:0xf bank_mask:0xf bound_ctrl:1
	v_add_f32_dpp v49, v49, v49 quad_perm:[1,0,3,2] row_mask:0xf bank_mask:0xf bound_ctrl:1
	v_add_f32_dpp v45, v45, v45 row_mirror row_mask:0xf bank_mask:0xf bound_ctrl:1
	v_add_f32_dpp v52, v52, v52 quad_perm:[2,3,0,1] row_mask:0xf bank_mask:0xf bound_ctrl:1
	s_waitcnt lgkmcnt(1)
	v_mul_f32_e32 v55, v31, v61
	v_fmac_f32_e32 v55, v30, v60
	v_add_f32_dpp v52, v52, v52 row_half_mirror row_mask:0xf bank_mask:0xf bound_ctrl:1
	v_add_f32_dpp v49, v49, v49 quad_perm:[2,3,0,1] row_mask:0xf bank_mask:0xf bound_ctrl:1
	v_mov_b32_e32 v47, v45
	v_add_f32_dpp v52, v52, v52 row_mirror row_mask:0xf bank_mask:0xf bound_ctrl:1
	v_mov_b32_e32 v53, v52
	s_nop 1
	v_permlane16_swap_b32_e32 v52, v53
	v_add_f32_e32 v52, v52, v53
	v_mul_f32_e32 v53, v29, v59
	v_fmac_f32_e32 v53, v28, v58
	ds_read_b128 v[58:61], v57 offset:30720
	v_add_f32_e32 v53, v53, v55
	s_waitcnt lgkmcnt(1)
	v_mul_f32_e32 v55, v25, v63
	v_fmac_f32_e32 v55, v24, v62
	v_mul_f32_e32 v62, v27, v65
	v_fmac_f32_e32 v62, v26, v64
	v_add_f32_e32 v53, 0, v53
	v_add_f32_e32 v55, v55, v62
	ds_read_b128 v[62:65], v57 offset:31744
	v_add_f32_e32 v53, v53, v55
	s_waitcnt lgkmcnt(1)
	v_mul_f32_e32 v55, v21, v59
	v_fmac_f32_e32 v55, v20, v58
	v_mul_f32_e32 v58, v23, v61
	v_fmac_f32_e32 v58, v22, v60
	v_add_f32_e32 v55, v55, v58
	v_add_f32_e32 v53, v53, v55
	s_waitcnt lgkmcnt(0)
	v_mul_f32_e32 v55, v17, v63
	v_mul_f32_e32 v58, v19, v65
	v_fmac_f32_e32 v55, v16, v62
	v_fmac_f32_e32 v58, v18, v64
	v_add_f32_e32 v55, v55, v58
	v_add_f32_e32 v53, v53, v55
	v_add_f32_dpp v49, v49, v49 row_half_mirror row_mask:0xf bank_mask:0xf bound_ctrl:1
	v_permlane16_swap_b32_e32 v45, v47
	v_add_f32_dpp v53, v53, v53 quad_perm:[1,0,3,2] row_mask:0xf bank_mask:0xf bound_ctrl:1
	v_add_f32_dpp v49, v49, v49 row_mirror row_mask:0xf bank_mask:0xf bound_ctrl:1
	v_mov_b32_e32 v51, v49
	v_add_f32_dpp v53, v53, v53 quad_perm:[2,3,0,1] row_mask:0xf bank_mask:0xf bound_ctrl:1
	s_nop 0
	v_permlane16_swap_b32_e32 v49, v51
	v_add_f32_dpp v53, v53, v53 row_half_mirror row_mask:0xf bank_mask:0xf bound_ctrl:1
	v_add_f32_e32 v45, v45, v47
	v_add_f32_e32 v49, v49, v51
	v_add_f32_dpp v53, v53, v53 row_mirror row_mask:0xf bank_mask:0xf bound_ctrl:1
	v_mov_b32_e32 v55, v53
	s_nop 1
	v_permlane16_swap_b32_e32 v53, v55
	v_add_f32_e32 v53, v53, v55
	v_mov_b32_e32 v46, v44
	v_mov_b32_e32 v47, v45
	v_mov_b32_e32 v50, v48
	v_mov_b32_e32 v51, v49
	v_mov_b32_e32 v54, v52
	v_mov_b32_e32 v55, v53
	v_permlane32_swap_b32_e32 v41, v43
	v_permlane32_swap_b32_e32 v44, v46
	v_permlane32_swap_b32_e32 v45, v47
	v_permlane32_swap_b32_e32 v48, v50
	v_permlane32_swap_b32_e32 v49, v51
	v_permlane32_swap_b32_e32 v52, v54
	v_permlane32_swap_b32_e32 v53, v55
	s_and_saveexec_b64 s[8:9], vcc
	s_cbranch_execz .LBB0_39
	s_lshl_b64 s[16:17], s[46:47], 5
	v_pk_add_f32 v[40:41], v[40:41], v[42:43]
	v_pk_add_f32 v[42:43], v[44:45], v[46:47]
	s_add_u32 s16, s4, s16
	v_pk_mul_f32 v[42:43], v[32:33], v[42:43] op_sel_hi:[0,1]
	v_pk_mul_f32 v[40:41], v[32:33], v[40:41] op_sel_hi:[0,1]
	v_pk_add_f32 v[44:45], v[48:49], v[50:51]
	v_pk_add_f32 v[46:47], v[52:53], v[54:55]
	s_addc_u32 s17, s5, s17
	v_pk_mul_f32 v[46:47], v[32:33], v[46:47] op_sel_hi:[0,1]
	v_pk_mul_f32 v[44:45], v[32:33], v[44:45] op_sel_hi:[0,1]
	global_store_dwordx4 v33, v[40:43], s[16:17]
	global_store_dwordx4 v33, v[44:47], s[16:17] offset:16
